# P4 scan: decay factors staged in LDS (ds_read_b64), chunk-product loads three groups ahead
# baseline (speedup 1.0000x reference)
.LBB0_351:
	s_waitcnt lgkmcnt(0)
	v_lshl_add_u64 v[10:11], s[34:35], 0, v[8:9]
	s_mov_b32 s4, 0x80000
	s_mov_b32 s5, 0
	s_mov_b32 s8, 0xb000000
	s_mov_b32 s9, 0
	s_mov_b32 s10, 0x2000000
	s_mov_b32 s11, 0
	v_lshl_add_u64 v[16:17], s[8:9], 0, v[10:11]
	v_lshl_add_u64 v[18:19], s[10:11], 0, v[10:11]
	v_mbcnt_lo_u32_b32 v88, -1, 0
	v_mbcnt_hi_u32_b32 v88, -1, v88
	s_lshl_b32 s6, s54, 6
	v_add_u32_e32 v89, s6, v88
	v_and_b32_e32 v90, 31, v89
	v_lshlrev_b32_e32 v90, 4, v90
	v_lshrrev_b32_e32 v91, 5, v89
	v_lshl_add_u32 v92, v91, 9, v90
	v_and_b32_e32 v93, 0xfffffe00, v6
	v_lshl_add_u32 v93, v91, 11, v93
	v_add_u32_e32 v93, v93, v90
	s_add_u32 s12, s34, 0xf00000
	s_addc_u32 s13, s35, 0
	global_load_dwordx4 v[56:59], v93, s[12:13]
	v_add_u32_e32 v93, 0x8000, v93
	global_load_dwordx4 v[60:63], v93, s[12:13]
	v_add_u32_e32 v93, 0x8000, v93
	global_load_dwordx4 v[64:67], v93, s[12:13]
	v_add_u32_e32 v93, 0x8000, v93
	global_load_dwordx4 v[68:71], v93, s[12:13]
	v_lshlrev_b32_e32 v88, 3, v88
	global_load_dword v24, v[16:17], off
	v_lshl_add_u64 v[16:17], s[4:5], 0, v[16:17]
	global_load_dword v25, v[16:17], off
	v_lshl_add_u64 v[16:17], s[4:5], 0, v[16:17]
	global_load_dword v26, v[16:17], off
	v_lshl_add_u64 v[16:17], s[4:5], 0, v[16:17]
	global_load_dword v27, v[16:17], off
	v_lshl_add_u64 v[16:17], s[4:5], 0, v[16:17]
	global_load_dword v28, v[16:17], off
	v_lshl_add_u64 v[16:17], s[4:5], 0, v[16:17]
	global_load_dword v29, v[16:17], off
	v_lshl_add_u64 v[16:17], s[4:5], 0, v[16:17]
	global_load_dword v30, v[16:17], off
	v_lshl_add_u64 v[16:17], s[4:5], 0, v[16:17]
	global_load_dword v31, v[16:17], off
	v_lshl_add_u64 v[16:17], s[4:5], 0, v[16:17]
	global_load_dword v32, v[16:17], off
	v_lshl_add_u64 v[16:17], s[4:5], 0, v[16:17]
	global_load_dword v33, v[16:17], off
	v_lshl_add_u64 v[16:17], s[4:5], 0, v[16:17]
	global_load_dword v34, v[16:17], off
	v_lshl_add_u64 v[16:17], s[4:5], 0, v[16:17]
	global_load_dword v35, v[16:17], off
	v_lshl_add_u64 v[16:17], s[4:5], 0, v[16:17]
	global_load_dword v36, v[16:17], off
	v_lshl_add_u64 v[16:17], s[4:5], 0, v[16:17]
	global_load_dword v37, v[16:17], off
	v_lshl_add_u64 v[16:17], s[4:5], 0, v[16:17]
	global_load_dword v38, v[16:17], off
	v_lshl_add_u64 v[16:17], s[4:5], 0, v[16:17]
	global_load_dword v39, v[16:17], off
	v_lshl_add_u64 v[16:17], s[4:5], 0, v[16:17]
	global_load_dword v40, v[16:17], off
	v_lshl_add_u64 v[16:17], s[4:5], 0, v[16:17]
	global_load_dword v41, v[16:17], off
	v_lshl_add_u64 v[16:17], s[4:5], 0, v[16:17]
	global_load_dword v42, v[16:17], off
	v_lshl_add_u64 v[16:17], s[4:5], 0, v[16:17]
	global_load_dword v43, v[16:17], off
	v_lshl_add_u64 v[16:17], s[4:5], 0, v[16:17]
	global_load_dword v44, v[16:17], off
	v_lshl_add_u64 v[16:17], s[4:5], 0, v[16:17]
	global_load_dword v45, v[16:17], off
	v_lshl_add_u64 v[16:17], s[4:5], 0, v[16:17]
	global_load_dword v46, v[16:17], off
	v_lshl_add_u64 v[16:17], s[4:5], 0, v[16:17]
	global_load_dword v47, v[16:17], off
	v_lshl_add_u64 v[16:17], s[4:5], 0, v[16:17]
	s_waitcnt vmcnt(24)
	ds_write_b128 v92, v[56:59]
	ds_write_b128 v92, v[60:63] offset:8192
	ds_write_b128 v92, v[64:67] offset:16384
	ds_write_b128 v92, v[68:71] offset:24576
	s_waitcnt lgkmcnt(0)
	s_barrier
	ds_read_b64 v[56:57], v88 offset:0
	ds_read_b64 v[58:59], v88 offset:512
	ds_read_b64 v[60:61], v88 offset:1024
	ds_read_b64 v[62:63], v88 offset:1536
	v_mov_b32_e32 v12, 0
	v_mov_b32_e32 v13, 0
	ds_read_b64 v[64:65], v88 offset:2048
	v_cvt_pk_bf16_f32 v98, v12, v13
	global_store_dword v[18:19], v98, off
	v_lshl_add_u64 v[18:19], s[4:5], 0, v[18:19]
	s_waitcnt vmcnt(24)
	v_lshlrev_b32_e32 v22, 16, v24
	v_and_b32_e32 v23, 0xffff0000, v24
	v_add_f32_e32 v12, v12, v22
	v_add_f32_e32 v13, v13, v23
	s_waitcnt lgkmcnt(4)
	v_mul_f32_e32 v96, v56, v12
	v_mul_f32_e32 v97, v57, v13
	s_waitcnt vmcnt(23)
	v_lshlrev_b32_e32 v22, 16, v25
	v_and_b32_e32 v23, 0xffff0000, v25
	v_fma_f32 v12, v56, v12, v22
	v_fma_f32 v13, v57, v13, v23
	v_cvt_pk_bf16_f32 v98, v96, v97
	global_store_dword v[18:19], v98, off
	v_lshl_add_u64 v[18:19], s[4:5], 0, v[18:19]
	ds_read_b64 v[66:67], v88 offset:2560
	s_waitcnt lgkmcnt(4)
	v_mul_f32_e32 v96, v58, v12
	v_mul_f32_e32 v97, v59, v13
	s_waitcnt vmcnt(23)
	v_lshlrev_b32_e32 v22, 16, v26
	v_and_b32_e32 v23, 0xffff0000, v26
	v_fma_f32 v12, v58, v12, v22
	v_fma_f32 v13, v59, v13, v23
	v_cvt_pk_bf16_f32 v98, v96, v97
	global_store_dword v[18:19], v98, off
	v_lshl_add_u64 v[18:19], s[4:5], 0, v[18:19]
	ds_read_b64 v[68:69], v88 offset:3072
	s_waitcnt lgkmcnt(4)
	v_mul_f32_e32 v96, v60, v12
	v_mul_f32_e32 v97, v61, v13
	s_waitcnt vmcnt(23)
	v_lshlrev_b32_e32 v22, 16, v27
	v_and_b32_e32 v23, 0xffff0000, v27
	v_fma_f32 v12, v60, v12, v22
	v_fma_f32 v13, v61, v13, v23
	v_cvt_pk_bf16_f32 v98, v96, v97
	global_store_dword v[18:19], v98, off
	v_lshl_add_u64 v[18:19], s[4:5], 0, v[18:19]
	ds_read_b64 v[70:71], v88 offset:3584
	s_waitcnt lgkmcnt(4)
	v_mul_f32_e32 v96, v62, v12
	v_mul_f32_e32 v97, v63, v13
	s_waitcnt vmcnt(23)
	v_lshlrev_b32_e32 v22, 16, v28
	v_and_b32_e32 v23, 0xffff0000, v28
	v_fma_f32 v12, v62, v12, v22
	v_fma_f32 v13, v63, v13, v23
	v_cvt_pk_bf16_f32 v98, v96, v97
	global_store_dword v[18:19], v98, off
	v_lshl_add_u64 v[18:19], s[4:5], 0, v[18:19]
	global_load_dword v48, v[16:17], off
	v_lshl_add_u64 v[16:17], s[4:5], 0, v[16:17]
	global_load_dword v49, v[16:17], off
	v_lshl_add_u64 v[16:17], s[4:5], 0, v[16:17]
	global_load_dword v50, v[16:17], off
	v_lshl_add_u64 v[16:17], s[4:5], 0, v[16:17]
	global_load_dword v51, v[16:17], off
	v_lshl_add_u64 v[16:17], s[4:5], 0, v[16:17]
	global_load_dword v52, v[16:17], off
	v_lshl_add_u64 v[16:17], s[4:5], 0, v[16:17]
	global_load_dword v53, v[16:17], off
	v_lshl_add_u64 v[16:17], s[4:5], 0, v[16:17]
	global_load_dword v54, v[16:17], off
	v_lshl_add_u64 v[16:17], s[4:5], 0, v[16:17]
	global_load_dword v55, v[16:17], off
	v_lshl_add_u64 v[16:17], s[4:5], 0, v[16:17]
	ds_read_b64 v[72:73], v88 offset:4096
	s_waitcnt lgkmcnt(4)
	v_mul_f32_e32 v96, v64, v12
	v_mul_f32_e32 v97, v65, v13
	s_waitcnt vmcnt(31)
	v_lshlrev_b32_e32 v22, 16, v29
	v_and_b32_e32 v23, 0xffff0000, v29
	v_fma_f32 v12, v64, v12, v22
	v_fma_f32 v13, v65, v13, v23
	v_cvt_pk_bf16_f32 v98, v96, v97
	global_store_dword v[18:19], v98, off
	v_lshl_add_u64 v[18:19], s[4:5], 0, v[18:19]
	ds_read_b64 v[74:75], v88 offset:4608
	s_waitcnt lgkmcnt(4)
	v_mul_f32_e32 v96, v66, v12
	v_mul_f32_e32 v97, v67, v13
	s_waitcnt vmcnt(31)
	v_lshlrev_b32_e32 v22, 16, v30
	v_and_b32_e32 v23, 0xffff0000, v30
	v_fma_f32 v12, v66, v12, v22
	v_fma_f32 v13, v67, v13, v23
	v_cvt_pk_bf16_f32 v98, v96, v97
	global_store_dword v[18:19], v98, off
	v_lshl_add_u64 v[18:19], s[4:5], 0, v[18:19]
	ds_read_b64 v[76:77], v88 offset:5120
	s_waitcnt lgkmcnt(4)
	v_mul_f32_e32 v96, v68, v12
	v_mul_f32_e32 v97, v69, v13
	s_waitcnt vmcnt(31)
	v_lshlrev_b32_e32 v22, 16, v31
	v_and_b32_e32 v23, 0xffff0000, v31
	v_fma_f32 v12, v68, v12, v22
	v_fma_f32 v13, v69, v13, v23
	v_cvt_pk_bf16_f32 v98, v96, v97
	global_store_dword v[18:19], v98, off
	v_lshl_add_u64 v[18:19], s[4:5], 0, v[18:19]
	ds_read_b64 v[78:79], v88 offset:5632
	s_waitcnt lgkmcnt(4)
	v_mul_f32_e32 v12, v70, v12
	v_mul_f32_e32 v13, v71, v13
	ds_read_b64 v[80:81], v88 offset:6144
	v_cvt_pk_bf16_f32 v98, v12, v13
	global_store_dword v[18:19], v98, off
	v_lshl_add_u64 v[18:19], s[4:5], 0, v[18:19]
	s_waitcnt vmcnt(32)
	v_lshlrev_b32_e32 v22, 16, v32
	v_and_b32_e32 v23, 0xffff0000, v32
	v_add_f32_e32 v12, v12, v22
	v_add_f32_e32 v13, v13, v23
	s_waitcnt lgkmcnt(4)
	v_mul_f32_e32 v96, v72, v12
	v_mul_f32_e32 v97, v73, v13
	s_waitcnt vmcnt(31)
	v_lshlrev_b32_e32 v22, 16, v33
	v_and_b32_e32 v23, 0xffff0000, v33
	v_fma_f32 v12, v72, v12, v22
	v_fma_f32 v13, v73, v13, v23
	v_cvt_pk_bf16_f32 v98, v96, v97
	global_store_dword v[18:19], v98, off
	v_lshl_add_u64 v[18:19], s[4:5], 0, v[18:19]
	ds_read_b64 v[82:83], v88 offset:6656
	s_waitcnt lgkmcnt(4)
	v_mul_f32_e32 v96, v74, v12
	v_mul_f32_e32 v97, v75, v13
	s_waitcnt vmcnt(31)
	v_lshlrev_b32_e32 v22, 16, v34
	v_and_b32_e32 v23, 0xffff0000, v34
	v_fma_f32 v12, v74, v12, v22
	v_fma_f32 v13, v75, v13, v23
	v_cvt_pk_bf16_f32 v98, v96, v97
	global_store_dword v[18:19], v98, off
	v_lshl_add_u64 v[18:19], s[4:5], 0, v[18:19]
	ds_read_b64 v[84:85], v88 offset:7168
	s_waitcnt lgkmcnt(4)
	v_mul_f32_e32 v96, v76, v12
	v_mul_f32_e32 v97, v77, v13
	s_waitcnt vmcnt(31)
	v_lshlrev_b32_e32 v22, 16, v35
	v_and_b32_e32 v23, 0xffff0000, v35
	v_fma_f32 v12, v76, v12, v22
	v_fma_f32 v13, v77, v13, v23
	v_cvt_pk_bf16_f32 v98, v96, v97
	global_store_dword v[18:19], v98, off
	v_lshl_add_u64 v[18:19], s[4:5], 0, v[18:19]
	ds_read_b64 v[86:87], v88 offset:7680
	s_waitcnt lgkmcnt(4)
	v_mul_f32_e32 v96, v78, v12
	v_mul_f32_e32 v97, v79, v13
	s_waitcnt vmcnt(31)
	v_lshlrev_b32_e32 v22, 16, v36
	v_and_b32_e32 v23, 0xffff0000, v36
	v_fma_f32 v12, v78, v12, v22
	v_fma_f32 v13, v79, v13, v23
	v_cvt_pk_bf16_f32 v98, v96, v97
	global_store_dword v[18:19], v98, off
	v_lshl_add_u64 v[18:19], s[4:5], 0, v[18:19]
	global_load_dword v24, v[16:17], off
	v_lshl_add_u64 v[16:17], s[4:5], 0, v[16:17]
	global_load_dword v25, v[16:17], off
	v_lshl_add_u64 v[16:17], s[4:5], 0, v[16:17]
	global_load_dword v26, v[16:17], off
	v_lshl_add_u64 v[16:17], s[4:5], 0, v[16:17]
	global_load_dword v27, v[16:17], off
	v_lshl_add_u64 v[16:17], s[4:5], 0, v[16:17]
	global_load_dword v28, v[16:17], off
	v_lshl_add_u64 v[16:17], s[4:5], 0, v[16:17]
	global_load_dword v29, v[16:17], off
	v_lshl_add_u64 v[16:17], s[4:5], 0, v[16:17]
	global_load_dword v30, v[16:17], off
	v_lshl_add_u64 v[16:17], s[4:5], 0, v[16:17]
	global_load_dword v31, v[16:17], off
	v_lshl_add_u64 v[16:17], s[4:5], 0, v[16:17]
	ds_read_b64 v[56:57], v88 offset:8192
	s_waitcnt lgkmcnt(4)
	v_mul_f32_e32 v96, v80, v12
	v_mul_f32_e32 v97, v81, v13
	s_waitcnt vmcnt(39)
	v_lshlrev_b32_e32 v22, 16, v37
	v_and_b32_e32 v23, 0xffff0000, v37
	v_fma_f32 v12, v80, v12, v22
	v_fma_f32 v13, v81, v13, v23
	v_cvt_pk_bf16_f32 v98, v96, v97
	global_store_dword v[18:19], v98, off
	v_lshl_add_u64 v[18:19], s[4:5], 0, v[18:19]
	ds_read_b64 v[58:59], v88 offset:8704
	s_waitcnt lgkmcnt(4)
	v_mul_f32_e32 v96, v82, v12
	v_mul_f32_e32 v97, v83, v13
	s_waitcnt vmcnt(39)
	v_lshlrev_b32_e32 v22, 16, v38
	v_and_b32_e32 v23, 0xffff0000, v38
	v_fma_f32 v12, v82, v12, v22
	v_fma_f32 v13, v83, v13, v23
	v_cvt_pk_bf16_f32 v98, v96, v97
	global_store_dword v[18:19], v98, off
	v_lshl_add_u64 v[18:19], s[4:5], 0, v[18:19]
	ds_read_b64 v[60:61], v88 offset:9216
	s_waitcnt lgkmcnt(4)
	v_mul_f32_e32 v96, v84, v12
	v_mul_f32_e32 v97, v85, v13
	s_waitcnt vmcnt(39)
	v_lshlrev_b32_e32 v22, 16, v39
	v_and_b32_e32 v23, 0xffff0000, v39
	v_fma_f32 v12, v84, v12, v22
	v_fma_f32 v13, v85, v13, v23
	v_cvt_pk_bf16_f32 v98, v96, v97
	global_store_dword v[18:19], v98, off
	v_lshl_add_u64 v[18:19], s[4:5], 0, v[18:19]
	ds_read_b64 v[62:63], v88 offset:9728
	s_waitcnt lgkmcnt(4)
	v_mul_f32_e32 v12, v86, v12
	v_mul_f32_e32 v13, v87, v13
	ds_read_b64 v[64:65], v88 offset:10240
	v_cvt_pk_bf16_f32 v98, v12, v13
	global_store_dword v[18:19], v98, off
	v_lshl_add_u64 v[18:19], s[4:5], 0, v[18:19]
	s_waitcnt vmcnt(40)
	v_lshlrev_b32_e32 v22, 16, v40
	v_and_b32_e32 v23, 0xffff0000, v40
	v_add_f32_e32 v12, v12, v22
	v_add_f32_e32 v13, v13, v23
	s_waitcnt lgkmcnt(4)
	v_mul_f32_e32 v96, v56, v12
	v_mul_f32_e32 v97, v57, v13
	s_waitcnt vmcnt(39)
	v_lshlrev_b32_e32 v22, 16, v41
	v_and_b32_e32 v23, 0xffff0000, v41
	v_fma_f32 v12, v56, v12, v22
	v_fma_f32 v13, v57, v13, v23
	v_cvt_pk_bf16_f32 v98, v96, v97
	global_store_dword v[18:19], v98, off
	v_lshl_add_u64 v[18:19], s[4:5], 0, v[18:19]
	ds_read_b64 v[66:67], v88 offset:10752
	s_waitcnt lgkmcnt(4)
	v_mul_f32_e32 v96, v58, v12
	v_mul_f32_e32 v97, v59, v13
	s_waitcnt vmcnt(39)
	v_lshlrev_b32_e32 v22, 16, v42
	v_and_b32_e32 v23, 0xffff0000, v42
	v_fma_f32 v12, v58, v12, v22
	v_fma_f32 v13, v59, v13, v23
	v_cvt_pk_bf16_f32 v98, v96, v97
	global_store_dword v[18:19], v98, off
	v_lshl_add_u64 v[18:19], s[4:5], 0, v[18:19]
	ds_read_b64 v[68:69], v88 offset:11264
	s_waitcnt lgkmcnt(4)
	v_mul_f32_e32 v96, v60, v12
	v_mul_f32_e32 v97, v61, v13
	s_waitcnt vmcnt(39)
	v_lshlrev_b32_e32 v22, 16, v43
	v_and_b32_e32 v23, 0xffff0000, v43
	v_fma_f32 v12, v60, v12, v22
	v_fma_f32 v13, v61, v13, v23
	v_cvt_pk_bf16_f32 v98, v96, v97
	global_store_dword v[18:19], v98, off
	v_lshl_add_u64 v[18:19], s[4:5], 0, v[18:19]
	ds_read_b64 v[70:71], v88 offset:11776
	s_waitcnt lgkmcnt(4)
	v_mul_f32_e32 v96, v62, v12
	v_mul_f32_e32 v97, v63, v13
	s_waitcnt vmcnt(39)
	v_lshlrev_b32_e32 v22, 16, v44
	v_and_b32_e32 v23, 0xffff0000, v44
	v_fma_f32 v12, v62, v12, v22
	v_fma_f32 v13, v63, v13, v23
	v_cvt_pk_bf16_f32 v98, v96, v97
	global_store_dword v[18:19], v98, off
	v_lshl_add_u64 v[18:19], s[4:5], 0, v[18:19]
	global_load_dword v32, v[16:17], off
	v_lshl_add_u64 v[16:17], s[4:5], 0, v[16:17]
	global_load_dword v33, v[16:17], off
	v_lshl_add_u64 v[16:17], s[4:5], 0, v[16:17]
	global_load_dword v34, v[16:17], off
	v_lshl_add_u64 v[16:17], s[4:5], 0, v[16:17]
	global_load_dword v35, v[16:17], off
	v_lshl_add_u64 v[16:17], s[4:5], 0, v[16:17]
	global_load_dword v36, v[16:17], off
	v_lshl_add_u64 v[16:17], s[4:5], 0, v[16:17]
	global_load_dword v37, v[16:17], off
	v_lshl_add_u64 v[16:17], s[4:5], 0, v[16:17]
	global_load_dword v38, v[16:17], off
	v_lshl_add_u64 v[16:17], s[4:5], 0, v[16:17]
	global_load_dword v39, v[16:17], off
	v_lshl_add_u64 v[16:17], s[4:5], 0, v[16:17]
	ds_read_b64 v[72:73], v88 offset:12288
	s_waitcnt lgkmcnt(4)
	v_mul_f32_e32 v96, v64, v12
	v_mul_f32_e32 v97, v65, v13
	s_waitcnt vmcnt(47)
	v_lshlrev_b32_e32 v22, 16, v45
	v_and_b32_e32 v23, 0xffff0000, v45
	v_fma_f32 v12, v64, v12, v22
	v_fma_f32 v13, v65, v13, v23
	v_cvt_pk_bf16_f32 v98, v96, v97
	global_store_dword v[18:19], v98, off
	v_lshl_add_u64 v[18:19], s[4:5], 0, v[18:19]
	ds_read_b64 v[74:75], v88 offset:12800
	s_waitcnt lgkmcnt(4)
	v_mul_f32_e32 v96, v66, v12
	v_mul_f32_e32 v97, v67, v13
	s_waitcnt vmcnt(47)
	v_lshlrev_b32_e32 v22, 16, v46
	v_and_b32_e32 v23, 0xffff0000, v46
	v_fma_f32 v12, v66, v12, v22
	v_fma_f32 v13, v67, v13, v23
	v_cvt_pk_bf16_f32 v98, v96, v97
	global_store_dword v[18:19], v98, off
	v_lshl_add_u64 v[18:19], s[4:5], 0, v[18:19]
	ds_read_b64 v[76:77], v88 offset:13312
	s_waitcnt lgkmcnt(4)
	v_mul_f32_e32 v96, v68, v12
	v_mul_f32_e32 v97, v69, v13
	s_waitcnt vmcnt(47)
	v_lshlrev_b32_e32 v22, 16, v47
	v_and_b32_e32 v23, 0xffff0000, v47
	v_fma_f32 v12, v68, v12, v22
	v_fma_f32 v13, v69, v13, v23
	v_cvt_pk_bf16_f32 v98, v96, v97
	global_store_dword v[18:19], v98, off
	v_lshl_add_u64 v[18:19], s[4:5], 0, v[18:19]
	ds_read_b64 v[78:79], v88 offset:13824
	s_waitcnt lgkmcnt(4)
	v_mul_f32_e32 v12, v70, v12
	v_mul_f32_e32 v13, v71, v13
	ds_read_b64 v[80:81], v88 offset:14336
	v_cvt_pk_bf16_f32 v98, v12, v13
	global_store_dword v[18:19], v98, off
	v_lshl_add_u64 v[18:19], s[4:5], 0, v[18:19]
	s_waitcnt vmcnt(43)
	v_lshlrev_b32_e32 v22, 16, v48
	v_and_b32_e32 v23, 0xffff0000, v48
	v_add_f32_e32 v12, v12, v22
	v_add_f32_e32 v13, v13, v23
	s_waitcnt lgkmcnt(4)
	v_mul_f32_e32 v96, v72, v12
	v_mul_f32_e32 v97, v73, v13
	s_waitcnt vmcnt(42)
	v_lshlrev_b32_e32 v22, 16, v49
	v_and_b32_e32 v23, 0xffff0000, v49
	v_fma_f32 v12, v72, v12, v22
	v_fma_f32 v13, v73, v13, v23
	v_cvt_pk_bf16_f32 v98, v96, v97
	global_store_dword v[18:19], v98, off
	v_lshl_add_u64 v[18:19], s[4:5], 0, v[18:19]
	ds_read_b64 v[82:83], v88 offset:14848
	s_waitcnt lgkmcnt(4)
	v_mul_f32_e32 v96, v74, v12
	v_mul_f32_e32 v97, v75, v13
	s_waitcnt vmcnt(42)
	v_lshlrev_b32_e32 v22, 16, v50
	v_and_b32_e32 v23, 0xffff0000, v50
	v_fma_f32 v12, v74, v12, v22
	v_fma_f32 v13, v75, v13, v23
	v_cvt_pk_bf16_f32 v98, v96, v97
	global_store_dword v[18:19], v98, off
	v_lshl_add_u64 v[18:19], s[4:5], 0, v[18:19]
	ds_read_b64 v[84:85], v88 offset:15360
	s_waitcnt lgkmcnt(4)
	v_mul_f32_e32 v96, v76, v12
	v_mul_f32_e32 v97, v77, v13
	s_waitcnt vmcnt(42)
	v_lshlrev_b32_e32 v22, 16, v51
	v_and_b32_e32 v23, 0xffff0000, v51
	v_fma_f32 v12, v76, v12, v22
	v_fma_f32 v13, v77, v13, v23
	v_cvt_pk_bf16_f32 v98, v96, v97
	global_store_dword v[18:19], v98, off
	v_lshl_add_u64 v[18:19], s[4:5], 0, v[18:19]
	ds_read_b64 v[86:87], v88 offset:15872
	s_waitcnt lgkmcnt(4)
	v_mul_f32_e32 v96, v78, v12
	v_mul_f32_e32 v97, v79, v13
	s_waitcnt vmcnt(42)
	v_lshlrev_b32_e32 v22, 16, v52
	v_and_b32_e32 v23, 0xffff0000, v52
	v_fma_f32 v12, v78, v12, v22
	v_fma_f32 v13, v79, v13, v23
	v_cvt_pk_bf16_f32 v98, v96, v97
	global_store_dword v[18:19], v98, off
	v_lshl_add_u64 v[18:19], s[4:5], 0, v[18:19]
	global_load_dword v40, v[16:17], off
	v_lshl_add_u64 v[16:17], s[4:5], 0, v[16:17]
	global_load_dword v41, v[16:17], off
	v_lshl_add_u64 v[16:17], s[4:5], 0, v[16:17]
	global_load_dword v42, v[16:17], off
	v_lshl_add_u64 v[16:17], s[4:5], 0, v[16:17]
	global_load_dword v43, v[16:17], off
	v_lshl_add_u64 v[16:17], s[4:5], 0, v[16:17]
	global_load_dword v44, v[16:17], off
	v_lshl_add_u64 v[16:17], s[4:5], 0, v[16:17]
	global_load_dword v45, v[16:17], off
	v_lshl_add_u64 v[16:17], s[4:5], 0, v[16:17]
	global_load_dword v46, v[16:17], off
	v_lshl_add_u64 v[16:17], s[4:5], 0, v[16:17]
	global_load_dword v47, v[16:17], off
	v_lshl_add_u64 v[16:17], s[4:5], 0, v[16:17]
	ds_read_b64 v[56:57], v88 offset:16384
	s_waitcnt lgkmcnt(4)
	v_mul_f32_e32 v96, v80, v12
	v_mul_f32_e32 v97, v81, v13
	s_waitcnt vmcnt(50)
	v_lshlrev_b32_e32 v22, 16, v53
	v_and_b32_e32 v23, 0xffff0000, v53
	v_fma_f32 v12, v80, v12, v22
	v_fma_f32 v13, v81, v13, v23
	v_cvt_pk_bf16_f32 v98, v96, v97
	global_store_dword v[18:19], v98, off
	v_lshl_add_u64 v[18:19], s[4:5], 0, v[18:19]
	ds_read_b64 v[58:59], v88 offset:16896
	s_waitcnt lgkmcnt(4)
	v_mul_f32_e32 v96, v82, v12
	v_mul_f32_e32 v97, v83, v13
	s_waitcnt vmcnt(50)
	v_lshlrev_b32_e32 v22, 16, v54
	v_and_b32_e32 v23, 0xffff0000, v54
	v_fma_f32 v12, v82, v12, v22
	v_fma_f32 v13, v83, v13, v23
	v_cvt_pk_bf16_f32 v98, v96, v97
	global_store_dword v[18:19], v98, off
	v_lshl_add_u64 v[18:19], s[4:5], 0, v[18:19]
	ds_read_b64 v[60:61], v88 offset:17408
	s_waitcnt lgkmcnt(4)
	v_mul_f32_e32 v96, v84, v12
	v_mul_f32_e32 v97, v85, v13
	s_waitcnt vmcnt(50)
	v_lshlrev_b32_e32 v22, 16, v55
	v_and_b32_e32 v23, 0xffff0000, v55
	v_fma_f32 v12, v84, v12, v22
	v_fma_f32 v13, v85, v13, v23
	v_cvt_pk_bf16_f32 v98, v96, v97
	global_store_dword v[18:19], v98, off
	v_lshl_add_u64 v[18:19], s[4:5], 0, v[18:19]
	ds_read_b64 v[62:63], v88 offset:17920
	s_waitcnt lgkmcnt(4)
	v_mul_f32_e32 v12, v86, v12
	v_mul_f32_e32 v13, v87, v13
	ds_read_b64 v[64:65], v88 offset:18432
	v_cvt_pk_bf16_f32 v98, v12, v13
	global_store_dword v[18:19], v98, off
	v_lshl_add_u64 v[18:19], s[4:5], 0, v[18:19]
	s_waitcnt vmcnt(43)
	v_lshlrev_b32_e32 v22, 16, v24
	v_and_b32_e32 v23, 0xffff0000, v24
	v_add_f32_e32 v12, v12, v22
	v_add_f32_e32 v13, v13, v23
	s_waitcnt lgkmcnt(4)
	v_mul_f32_e32 v96, v56, v12
	v_mul_f32_e32 v97, v57, v13
	s_waitcnt vmcnt(42)
	v_lshlrev_b32_e32 v22, 16, v25
	v_and_b32_e32 v23, 0xffff0000, v25
	v_fma_f32 v12, v56, v12, v22
	v_fma_f32 v13, v57, v13, v23
	v_cvt_pk_bf16_f32 v98, v96, v97
	global_store_dword v[18:19], v98, off
	v_lshl_add_u64 v[18:19], s[4:5], 0, v[18:19]
	ds_read_b64 v[66:67], v88 offset:18944
	s_waitcnt lgkmcnt(4)
	v_mul_f32_e32 v96, v58, v12
	v_mul_f32_e32 v97, v59, v13
	s_waitcnt vmcnt(42)
	v_lshlrev_b32_e32 v22, 16, v26
	v_and_b32_e32 v23, 0xffff0000, v26
	v_fma_f32 v12, v58, v12, v22
	v_fma_f32 v13, v59, v13, v23
	v_cvt_pk_bf16_f32 v98, v96, v97
	global_store_dword v[18:19], v98, off
	v_lshl_add_u64 v[18:19], s[4:5], 0, v[18:19]
	ds_read_b64 v[68:69], v88 offset:19456
	s_waitcnt lgkmcnt(4)
	v_mul_f32_e32 v96, v60, v12
	v_mul_f32_e32 v97, v61, v13
	s_waitcnt vmcnt(42)
	v_lshlrev_b32_e32 v22, 16, v27
	v_and_b32_e32 v23, 0xffff0000, v27
	v_fma_f32 v12, v60, v12, v22
	v_fma_f32 v13, v61, v13, v23
	v_cvt_pk_bf16_f32 v98, v96, v97
	global_store_dword v[18:19], v98, off
	v_lshl_add_u64 v[18:19], s[4:5], 0, v[18:19]
	ds_read_b64 v[70:71], v88 offset:19968
	s_waitcnt lgkmcnt(4)
	v_mul_f32_e32 v96, v62, v12
	v_mul_f32_e32 v97, v63, v13
	s_waitcnt vmcnt(42)
	v_lshlrev_b32_e32 v22, 16, v28
	v_and_b32_e32 v23, 0xffff0000, v28
	v_fma_f32 v12, v62, v12, v22
	v_fma_f32 v13, v63, v13, v23
	v_cvt_pk_bf16_f32 v98, v96, v97
	global_store_dword v[18:19], v98, off
	v_lshl_add_u64 v[18:19], s[4:5], 0, v[18:19]
	global_load_dword v48, v[16:17], off
	v_lshl_add_u64 v[16:17], s[4:5], 0, v[16:17]
	global_load_dword v49, v[16:17], off
	v_lshl_add_u64 v[16:17], s[4:5], 0, v[16:17]
	global_load_dword v50, v[16:17], off
	v_lshl_add_u64 v[16:17], s[4:5], 0, v[16:17]
	global_load_dword v51, v[16:17], off
	v_lshl_add_u64 v[16:17], s[4:5], 0, v[16:17]
	global_load_dword v52, v[16:17], off
	v_lshl_add_u64 v[16:17], s[4:5], 0, v[16:17]
	global_load_dword v53, v[16:17], off
	v_lshl_add_u64 v[16:17], s[4:5], 0, v[16:17]
	global_load_dword v54, v[16:17], off
	v_lshl_add_u64 v[16:17], s[4:5], 0, v[16:17]
	global_load_dword v55, v[16:17], off
	v_lshl_add_u64 v[16:17], s[4:5], 0, v[16:17]
	ds_read_b64 v[72:73], v88 offset:20480
	s_waitcnt lgkmcnt(4)
	v_mul_f32_e32 v96, v64, v12
	v_mul_f32_e32 v97, v65, v13
	s_waitcnt vmcnt(50)
	v_lshlrev_b32_e32 v22, 16, v29
	v_and_b32_e32 v23, 0xffff0000, v29
	v_fma_f32 v12, v64, v12, v22
	v_fma_f32 v13, v65, v13, v23
	v_cvt_pk_bf16_f32 v98, v96, v97
	global_store_dword v[18:19], v98, off
	v_lshl_add_u64 v[18:19], s[4:5], 0, v[18:19]
	ds_read_b64 v[74:75], v88 offset:20992
	s_waitcnt lgkmcnt(4)
	v_mul_f32_e32 v96, v66, v12
	v_mul_f32_e32 v97, v67, v13
	s_waitcnt vmcnt(50)
	v_lshlrev_b32_e32 v22, 16, v30
	v_and_b32_e32 v23, 0xffff0000, v30
	v_fma_f32 v12, v66, v12, v22
	v_fma_f32 v13, v67, v13, v23
	v_cvt_pk_bf16_f32 v98, v96, v97
	global_store_dword v[18:19], v98, off
	v_lshl_add_u64 v[18:19], s[4:5], 0, v[18:19]
	ds_read_b64 v[76:77], v88 offset:21504
	s_waitcnt lgkmcnt(4)
	v_mul_f32_e32 v96, v68, v12
	v_mul_f32_e32 v97, v69, v13
	s_waitcnt vmcnt(50)
	v_lshlrev_b32_e32 v22, 16, v31
	v_and_b32_e32 v23, 0xffff0000, v31
	v_fma_f32 v12, v68, v12, v22
	v_fma_f32 v13, v69, v13, v23
	v_cvt_pk_bf16_f32 v98, v96, v97
	global_store_dword v[18:19], v98, off
	v_lshl_add_u64 v[18:19], s[4:5], 0, v[18:19]
	ds_read_b64 v[78:79], v88 offset:22016
	s_waitcnt lgkmcnt(4)
	v_mul_f32_e32 v12, v70, v12
	v_mul_f32_e32 v13, v71, v13
	ds_read_b64 v[80:81], v88 offset:22528
	v_cvt_pk_bf16_f32 v98, v12, v13
	global_store_dword v[18:19], v98, off
	v_lshl_add_u64 v[18:19], s[4:5], 0, v[18:19]
	s_waitcnt vmcnt(43)
	v_lshlrev_b32_e32 v22, 16, v32
	v_and_b32_e32 v23, 0xffff0000, v32
	v_add_f32_e32 v12, v12, v22
	v_add_f32_e32 v13, v13, v23
	s_waitcnt lgkmcnt(4)
	v_mul_f32_e32 v96, v72, v12
	v_mul_f32_e32 v97, v73, v13
	s_waitcnt vmcnt(42)
	v_lshlrev_b32_e32 v22, 16, v33
	v_and_b32_e32 v23, 0xffff0000, v33
	v_fma_f32 v12, v72, v12, v22
	v_fma_f32 v13, v73, v13, v23
	v_cvt_pk_bf16_f32 v98, v96, v97
	global_store_dword v[18:19], v98, off
	v_lshl_add_u64 v[18:19], s[4:5], 0, v[18:19]
	ds_read_b64 v[82:83], v88 offset:23040
	s_waitcnt lgkmcnt(4)
	v_mul_f32_e32 v96, v74, v12
	v_mul_f32_e32 v97, v75, v13
	s_waitcnt vmcnt(42)
	v_lshlrev_b32_e32 v22, 16, v34
	v_and_b32_e32 v23, 0xffff0000, v34
	v_fma_f32 v12, v74, v12, v22
	v_fma_f32 v13, v75, v13, v23
	v_cvt_pk_bf16_f32 v98, v96, v97
	global_store_dword v[18:19], v98, off
	v_lshl_add_u64 v[18:19], s[4:5], 0, v[18:19]
	ds_read_b64 v[84:85], v88 offset:23552
	s_waitcnt lgkmcnt(4)
	v_mul_f32_e32 v96, v76, v12
	v_mul_f32_e32 v97, v77, v13
	s_waitcnt vmcnt(42)
	v_lshlrev_b32_e32 v22, 16, v35
	v_and_b32_e32 v23, 0xffff0000, v35
	v_fma_f32 v12, v76, v12, v22
	v_fma_f32 v13, v77, v13, v23
	v_cvt_pk_bf16_f32 v98, v96, v97
	global_store_dword v[18:19], v98, off
	v_lshl_add_u64 v[18:19], s[4:5], 0, v[18:19]
	ds_read_b64 v[86:87], v88 offset:24064
	s_waitcnt lgkmcnt(4)
	v_mul_f32_e32 v96, v78, v12
	v_mul_f32_e32 v97, v79, v13
	s_waitcnt vmcnt(42)
	v_lshlrev_b32_e32 v22, 16, v36
	v_and_b32_e32 v23, 0xffff0000, v36
	v_fma_f32 v12, v78, v12, v22
	v_fma_f32 v13, v79, v13, v23
	v_cvt_pk_bf16_f32 v98, v96, v97
	global_store_dword v[18:19], v98, off
	v_lshl_add_u64 v[18:19], s[4:5], 0, v[18:19]
	ds_read_b64 v[56:57], v88 offset:24576
	s_waitcnt lgkmcnt(4)
	v_mul_f32_e32 v96, v80, v12
	v_mul_f32_e32 v97, v81, v13
	s_waitcnt vmcnt(42)
	v_lshlrev_b32_e32 v22, 16, v37
	v_and_b32_e32 v23, 0xffff0000, v37
	v_fma_f32 v12, v80, v12, v22
	v_fma_f32 v13, v81, v13, v23
	v_cvt_pk_bf16_f32 v98, v96, v97
	global_store_dword v[18:19], v98, off
	v_lshl_add_u64 v[18:19], s[4:5], 0, v[18:19]
	ds_read_b64 v[58:59], v88 offset:25088
	s_waitcnt lgkmcnt(4)
	v_mul_f32_e32 v96, v82, v12
	v_mul_f32_e32 v97, v83, v13
	s_waitcnt vmcnt(42)
	v_lshlrev_b32_e32 v22, 16, v38
	v_and_b32_e32 v23, 0xffff0000, v38
	v_fma_f32 v12, v82, v12, v22
	v_fma_f32 v13, v83, v13, v23
	v_cvt_pk_bf16_f32 v98, v96, v97
	global_store_dword v[18:19], v98, off
	v_lshl_add_u64 v[18:19], s[4:5], 0, v[18:19]
	ds_read_b64 v[60:61], v88 offset:25600
	s_waitcnt lgkmcnt(4)
	v_mul_f32_e32 v96, v84, v12
	v_mul_f32_e32 v97, v85, v13
	s_waitcnt vmcnt(42)
	v_lshlrev_b32_e32 v22, 16, v39
	v_and_b32_e32 v23, 0xffff0000, v39
	v_fma_f32 v12, v84, v12, v22
	v_fma_f32 v13, v85, v13, v23
	v_cvt_pk_bf16_f32 v98, v96, v97
	global_store_dword v[18:19], v98, off
	v_lshl_add_u64 v[18:19], s[4:5], 0, v[18:19]
	ds_read_b64 v[62:63], v88 offset:26112
	s_waitcnt lgkmcnt(4)
	v_mul_f32_e32 v12, v86, v12
	v_mul_f32_e32 v13, v87, v13
	ds_read_b64 v[64:65], v88 offset:26624
	v_cvt_pk_bf16_f32 v98, v12, v13
	global_store_dword v[18:19], v98, off
	v_lshl_add_u64 v[18:19], s[4:5], 0, v[18:19]
	s_waitcnt vmcnt(35)
	v_lshlrev_b32_e32 v22, 16, v40
	v_and_b32_e32 v23, 0xffff0000, v40
	v_add_f32_e32 v12, v12, v22
	v_add_f32_e32 v13, v13, v23
	s_waitcnt lgkmcnt(4)
	v_mul_f32_e32 v96, v56, v12
	v_mul_f32_e32 v97, v57, v13
	s_waitcnt vmcnt(34)
	v_lshlrev_b32_e32 v22, 16, v41
	v_and_b32_e32 v23, 0xffff0000, v41
	v_fma_f32 v12, v56, v12, v22
	v_fma_f32 v13, v57, v13, v23
	v_cvt_pk_bf16_f32 v98, v96, v97
	global_store_dword v[18:19], v98, off
	v_lshl_add_u64 v[18:19], s[4:5], 0, v[18:19]
	ds_read_b64 v[66:67], v88 offset:27136
	s_waitcnt lgkmcnt(4)
	v_mul_f32_e32 v96, v58, v12
	v_mul_f32_e32 v97, v59, v13
	s_waitcnt vmcnt(34)
	v_lshlrev_b32_e32 v22, 16, v42
	v_and_b32_e32 v23, 0xffff0000, v42
	v_fma_f32 v12, v58, v12, v22
	v_fma_f32 v13, v59, v13, v23
	v_cvt_pk_bf16_f32 v98, v96, v97
	global_store_dword v[18:19], v98, off
	v_lshl_add_u64 v[18:19], s[4:5], 0, v[18:19]
	ds_read_b64 v[68:69], v88 offset:27648
	s_waitcnt lgkmcnt(4)
	v_mul_f32_e32 v96, v60, v12
	v_mul_f32_e32 v97, v61, v13
	s_waitcnt vmcnt(34)
	v_lshlrev_b32_e32 v22, 16, v43
	v_and_b32_e32 v23, 0xffff0000, v43
	v_fma_f32 v12, v60, v12, v22
	v_fma_f32 v13, v61, v13, v23
	v_cvt_pk_bf16_f32 v98, v96, v97
	global_store_dword v[18:19], v98, off
	v_lshl_add_u64 v[18:19], s[4:5], 0, v[18:19]
	ds_read_b64 v[70:71], v88 offset:28160
	s_waitcnt lgkmcnt(4)
	v_mul_f32_e32 v96, v62, v12
	v_mul_f32_e32 v97, v63, v13
	s_waitcnt vmcnt(34)
	v_lshlrev_b32_e32 v22, 16, v44
	v_and_b32_e32 v23, 0xffff0000, v44
	v_fma_f32 v12, v62, v12, v22
	v_fma_f32 v13, v63, v13, v23
	v_cvt_pk_bf16_f32 v98, v96, v97
	global_store_dword v[18:19], v98, off
	v_lshl_add_u64 v[18:19], s[4:5], 0, v[18:19]
	ds_read_b64 v[72:73], v88 offset:28672
	s_waitcnt lgkmcnt(4)
	v_mul_f32_e32 v96, v64, v12
	v_mul_f32_e32 v97, v65, v13
	s_waitcnt vmcnt(34)
	v_lshlrev_b32_e32 v22, 16, v45
	v_and_b32_e32 v23, 0xffff0000, v45
	v_fma_f32 v12, v64, v12, v22
	v_fma_f32 v13, v65, v13, v23
	v_cvt_pk_bf16_f32 v98, v96, v97
	global_store_dword v[18:19], v98, off
	v_lshl_add_u64 v[18:19], s[4:5], 0, v[18:19]
	ds_read_b64 v[74:75], v88 offset:29184
	s_waitcnt lgkmcnt(4)
	v_mul_f32_e32 v96, v66, v12
	v_mul_f32_e32 v97, v67, v13
	s_waitcnt vmcnt(34)
	v_lshlrev_b32_e32 v22, 16, v46
	v_and_b32_e32 v23, 0xffff0000, v46
	v_fma_f32 v12, v66, v12, v22
	v_fma_f32 v13, v67, v13, v23
	v_cvt_pk_bf16_f32 v98, v96, v97
	global_store_dword v[18:19], v98, off
	v_lshl_add_u64 v[18:19], s[4:5], 0, v[18:19]
	ds_read_b64 v[76:77], v88 offset:29696
	s_waitcnt lgkmcnt(4)
	v_mul_f32_e32 v96, v68, v12
	v_mul_f32_e32 v97, v69, v13
	s_waitcnt vmcnt(34)
	v_lshlrev_b32_e32 v22, 16, v47
	v_and_b32_e32 v23, 0xffff0000, v47
	v_fma_f32 v12, v68, v12, v22
	v_fma_f32 v13, v69, v13, v23
	v_cvt_pk_bf16_f32 v98, v96, v97
	global_store_dword v[18:19], v98, off
	v_lshl_add_u64 v[18:19], s[4:5], 0, v[18:19]
	ds_read_b64 v[78:79], v88 offset:30208
	s_waitcnt lgkmcnt(4)
	v_mul_f32_e32 v12, v70, v12
	v_mul_f32_e32 v13, v71, v13
	ds_read_b64 v[80:81], v88 offset:30720
	v_cvt_pk_bf16_f32 v98, v12, v13
	global_store_dword v[18:19], v98, off
	v_lshl_add_u64 v[18:19], s[4:5], 0, v[18:19]
	s_waitcnt vmcnt(27)
	v_lshlrev_b32_e32 v22, 16, v48
	v_and_b32_e32 v23, 0xffff0000, v48
	v_add_f32_e32 v12, v12, v22
	v_add_f32_e32 v13, v13, v23
	s_waitcnt lgkmcnt(4)
	v_mul_f32_e32 v96, v72, v12
	v_mul_f32_e32 v97, v73, v13
	s_waitcnt vmcnt(26)
	v_lshlrev_b32_e32 v22, 16, v49
	v_and_b32_e32 v23, 0xffff0000, v49
	v_fma_f32 v12, v72, v12, v22
	v_fma_f32 v13, v73, v13, v23
	v_cvt_pk_bf16_f32 v98, v96, v97
	global_store_dword v[18:19], v98, off
	v_lshl_add_u64 v[18:19], s[4:5], 0, v[18:19]
	ds_read_b64 v[82:83], v88 offset:31232
	s_waitcnt lgkmcnt(4)
	v_mul_f32_e32 v96, v74, v12
	v_mul_f32_e32 v97, v75, v13
	s_waitcnt vmcnt(26)
	v_lshlrev_b32_e32 v22, 16, v50
	v_and_b32_e32 v23, 0xffff0000, v50
	v_fma_f32 v12, v74, v12, v22
	v_fma_f32 v13, v75, v13, v23
	v_cvt_pk_bf16_f32 v98, v96, v97
	global_store_dword v[18:19], v98, off
	v_lshl_add_u64 v[18:19], s[4:5], 0, v[18:19]
	ds_read_b64 v[84:85], v88 offset:31744
	s_waitcnt lgkmcnt(4)
	v_mul_f32_e32 v96, v76, v12
	v_mul_f32_e32 v97, v77, v13
	s_waitcnt vmcnt(26)
	v_lshlrev_b32_e32 v22, 16, v51
	v_and_b32_e32 v23, 0xffff0000, v51
	v_fma_f32 v12, v76, v12, v22
	v_fma_f32 v13, v77, v13, v23
	v_cvt_pk_bf16_f32 v98, v96, v97
	global_store_dword v[18:19], v98, off
	v_lshl_add_u64 v[18:19], s[4:5], 0, v[18:19]
	ds_read_b64 v[86:87], v88 offset:32256
	s_waitcnt lgkmcnt(4)
	v_mul_f32_e32 v96, v78, v12
	v_mul_f32_e32 v97, v79, v13
	s_waitcnt vmcnt(26)
	v_lshlrev_b32_e32 v22, 16, v52
	v_and_b32_e32 v23, 0xffff0000, v52
	v_fma_f32 v12, v78, v12, v22
	v_fma_f32 v13, v79, v13, v23
	v_cvt_pk_bf16_f32 v98, v96, v97
	global_store_dword v[18:19], v98, off
	v_lshl_add_u64 v[18:19], s[4:5], 0, v[18:19]
	s_waitcnt lgkmcnt(3)
	v_mul_f32_e32 v96, v80, v12
	v_mul_f32_e32 v97, v81, v13
	s_waitcnt vmcnt(26)
	v_lshlrev_b32_e32 v22, 16, v53
	v_and_b32_e32 v23, 0xffff0000, v53
	v_fma_f32 v12, v80, v12, v22
	v_fma_f32 v13, v81, v13, v23
	v_cvt_pk_bf16_f32 v98, v96, v97
	global_store_dword v[18:19], v98, off
	v_lshl_add_u64 v[18:19], s[4:5], 0, v[18:19]
	s_waitcnt lgkmcnt(2)
	v_mul_f32_e32 v96, v82, v12
	v_mul_f32_e32 v97, v83, v13
	s_waitcnt vmcnt(26)
	v_lshlrev_b32_e32 v22, 16, v54
	v_and_b32_e32 v23, 0xffff0000, v54
	v_fma_f32 v12, v82, v12, v22
	v_fma_f32 v13, v83, v13, v23
	v_cvt_pk_bf16_f32 v98, v96, v97
	global_store_dword v[18:19], v98, off
	v_lshl_add_u64 v[18:19], s[4:5], 0, v[18:19]
	s_waitcnt lgkmcnt(1)
	v_mul_f32_e32 v96, v84, v12
	v_mul_f32_e32 v97, v85, v13
	s_waitcnt vmcnt(26)
	v_lshlrev_b32_e32 v22, 16, v55
	v_and_b32_e32 v23, 0xffff0000, v55
	v_fma_f32 v12, v84, v12, v22
	v_fma_f32 v13, v85, v13, v23
	v_cvt_pk_bf16_f32 v98, v96, v97
	global_store_dword v[18:19], v98, off
	v_lshl_add_u64 v[18:19], s[4:5], 0, v[18:19]
	s_waitcnt lgkmcnt(0)
	v_mul_f32_e32 v12, v86, v12
	v_mul_f32_e32 v13, v87, v13
	v_add_u32_e32 v2, s36, v2
	v_cmp_lt_i32_e32 vcc, s51, v2
	v_lshl_add_u64 v[4:5], v[4:5], 0, s[38:39]
	s_or_b64 s[44:45], vcc, s[44:45]
	v_add_u32_e32 v3, s37, v3
	s_andn2_b64 exec, exec, s[44:45]
	s_cbranch_execnz .LBB0_350
